# sample-stream RWKV scan replaced by the MFMA value-row scan variant (32 steps, initial state and S0*a0 term loaded)
# speedup vs baseline: 1.0416x; 1.0004x over previous
; __device__ __forceinline__ int bidx() { int b = blockIdx.x; asm volatile("" : "+s"(b)); return b; }
; #define INP(p, i) ldp((p).tbl, i)
; __device__ __forceinline__ float bf2f(unsigned short b) { return __uint_as_float((unsigned)b << 16); }
; __device__ __forceinline__ f2 pfma(f2 a, f2 b, f2 c) { return __builtin_elementwise_fma(a, b, c); }
; template <bool ID> __device__ __forceinline__ void rwkv_scan(const bf16_t* __restrict__ R, const bf16_t* __restrict__ EW, const bf16_t* __restrict__ K, const bf16_t* __restrict__ V, ...
;     ...
;     { unsigned o = base; q1[0] = R[o]; q1[1] = EW[o]; q1[2] = K[o]; q1[3] = V[o]; q1[4] = A[o]; q1[5] = B[o];
;       o = base + 512u; q2[0] = R[o]; q2[1] = EW[o]; q2[2] = K[o]; q2[3] = V[o]; q2[4] = A[o]; q2[5] = B[o]; }
;     const LAS f32x4* pa = (const LAS f32x4*)L;
;     float sav, sai;
;     { L[lane] = bf2f(q1[4]);
;       f2 av = {0.f, 0.f}, ai = {0.f, 0.f};
; #pragma unroll
;       for (int q = 0; q < 16; ++q) { const f32x4 a4 = pa[q]; const f2 a01 = {a4[0], a4[1]}, a23 = {a4[2], a4[3]};
;           av = pfma(Sv[2 * q], a01, av); av = pfma(Sv[2 * q + 1], a23, av); if (ID) { ai = pfma(Si[2 * q], a01, ai); ai = pfma(Si[2 * q + 1], a23, ai); } }
;       sav = av[0] + av[1]; sai = ai[0] + ai[1]; }
; __device__ void phase_rwkv_scan(const Ctx& p, int l, LAS unsigned char* lds) {
;     ...
;         for (int item = bidx(); item < 256; item += gridDim.x) {
;             const int s = item >> 3, h = item & 7;
;             const size_t so = (((size_t)l * 32 + s) * 8 + h) * 4096 + lane * 64;
;             f2 Sv[32], Si[32];
;             const float* sp = INP(p, 3) + so;
; #pragma unroll
;             for (int i = 0; i < 32; i += 2) { const float4 q = *(const float4*)(sp + 2 * i); Sv[i] = (f2){q.x, q.y}; Sv[i + 1] = (f2){q.z, q.w}; Si[i] = (f2){0.f, 0.f}; Si[i + 1] = (f2){0.f, 0.f}; }
;             rwkv_scan<false>(R, EW, K, V, A, B, (unsigned)((T_P + s * 32) * 512 + h * 64 + lane), 32, Sv, Si, YH, QH, L, lane);
.Lscan_s:
	v_lshrrev_b32_e32 v78, 5, v139
	v_and_b32_e32 v79, 31, v139
	s_mov_b32 s26, -1
	s_mov_b32 s27, 0
	v_mov_b64_e32 v[0:1], s[92:93]
	flat_load_dwordx2 v[0:1], v[0:1] offset:24 sc0 sc1
	s_waitcnt vmcnt(0) lgkmcnt(0)
	v_readfirstlane_b32 s14, v0
	v_readfirstlane_b32 s15, v1
	s_and_b64 s[36:37], s[34:35], exec
	s_cselect_b32 s36, 32, 0
	s_lshr_b32 s37, s90, 3
	s_add_i32 s36, s36, s37
	s_lshl_b32 s36, s36, 17
	s_and_b32 s37, s90, 7
	s_lshl_b32 s37, s37, 14
	s_or_b32 s36, s36, s37
	s_add_u32 s16, s14, s36
	s_addc_u32 s17, s15, 0
	v_readlane_b32 s14, v242, 1
	v_readlane_b32 s15, v242, 2
	s_add_u32 s36, s14, s36
	s_addc_u32 s37, s15, 0
	s_lshr_b32 s14, s90, 3
	s_lshl_b32 s14, s14, 14
	s_and_b32 s15, s90, 7
	s_lshl_b32 s15, s15, 6
	s_or_b32 s14, s14, s15
	s_add_i32 s14, s14, 0x800000
	v_add_lshl_u32 v72, s14, v139, 1
	v_add_lshl_u32 v81, s14, v79, 1
	v_mov_b32_e32 v74, s20
	v_mov_b32_e32 v75, s21
	v_mov_b32_e32 v80, s6
	v_cndmask_b32_e64 v74, v80, v74, s[26:27]
	v_mov_b32_e32 v80, s7
	v_cndmask_b32_e64 v75, v80, v75, s[26:27]
	v_add_co_u32_e32 v74, vcc, v74, v81
	s_nop 1
	v_addc_co_u32_e32 v75, vcc, 0, v75, vcc
	v_lshl_add_u32 v76, v78, 4, s10
	v_lshl_add_u32 v77, v139, 2, s10
	v_lshl_add_u32 v251, v79, 2, s10
	v_mov_b32_e32 v246, 1.0
	v_lshlrev_b32_e32 v81, 2, v78
	v_sub_u32_e32 v81, v79, v81
	global_load_ushort v254, v72, s[12:13]
	global_load_ushort v224, v72, s[4:5] offset:0
	global_load_ushort v225, v72, s[0:1] offset:0
	global_load_ushort v226, v72, s[12:13] offset:1024
	global_load_ushort v227, v[74:75], off offset:0
	global_load_ushort v228, v[74:75], off offset:64
	global_load_ushort v229, v72, s[2:3] offset:0
	global_load_ushort v230, v72, s[4:5] offset:1024
	global_load_ushort v231, v72, s[0:1] offset:1024
	global_load_ushort v232, v72, s[12:13] offset:2048
	global_load_ushort v233, v[74:75], off offset:1024
	global_load_ushort v234, v[74:75], off offset:1088
	global_load_ushort v235, v72, s[2:3] offset:1024
	global_load_ushort v82, v72, s[4:5] offset:2048
	global_load_ushort v83, v72, s[0:1] offset:2048
	global_load_ushort v84, v72, s[12:13] offset:3072
	global_load_ushort v85, v[74:75], off offset:2048
	global_load_ushort v86, v[74:75], off offset:2112
	global_load_ushort v87, v72, s[2:3] offset:2048
	v_add_u32_e32 v72, 0xc00, v72
	v_lshl_add_u64 v[74:75], v[74:75], 0, s[54:55]
	v_lshl_add_u64 v[74:75], v[74:75], 0, s[54:55]
	v_lshl_add_u64 v[74:75], v[74:75], 0, s[54:55]
	global_load_ushort v88, v72, s[4:5] offset:0
	global_load_ushort v89, v72, s[0:1] offset:0
	global_load_ushort v90, v72, s[12:13] offset:1024
	global_load_ushort v91, v[74:75], off offset:0
	global_load_ushort v92, v[74:75], off offset:64
	global_load_ushort v93, v72, s[2:3] offset:0
	v_add_u32_e32 v72, 0x400, v72
	v_lshl_add_u64 v[74:75], v[74:75], 0, s[54:55]
	v_lshlrev_b32_e32 v252, 8, v79
	v_lshl_add_u32 v252, v78, 4, v252
	v_add_u32_e32 v253, 0x2000, v252
	global_load_dwordx4 v[0:3], v252, s[16:17] offset:0
	global_load_dwordx4 v[4:7], v252, s[16:17] offset:32
	global_load_dwordx4 v[8:11], v252, s[16:17] offset:64
	global_load_dwordx4 v[12:15], v252, s[16:17] offset:96
	global_load_dwordx4 v[16:19], v252, s[16:17] offset:128
	global_load_dwordx4 v[20:23], v252, s[16:17] offset:160
	global_load_dwordx4 v[24:27], v252, s[16:17] offset:192
	global_load_dwordx4 v[28:31], v252, s[16:17] offset:224
	global_load_dwordx4 v[32:35], v253, s[16:17] offset:0
	global_load_dwordx4 v[36:39], v253, s[16:17] offset:32
	global_load_dwordx4 v[40:43], v253, s[16:17] offset:64
	global_load_dwordx4 v[44:47], v253, s[16:17] offset:96
	global_load_dwordx4 v[48:51], v253, s[16:17] offset:128
	global_load_dwordx4 v[52:55], v253, s[16:17] offset:160
	global_load_dwordx4 v[56:59], v253, s[16:17] offset:192
	global_load_dwordx4 v[60:63], v253, s[16:17] offset:224
	s_waitcnt vmcnt(0)
	v_lshlrev_b32_e32 v254, 16, v254
	ds_write_b32 v77, v254 offset:1280
	ds_write_b32 v77, v254 offset:1024
	ds_read_b128 v[148:151], v76 offset:1024
	ds_read_b128 v[152:155], v76 offset:1056
	ds_read_b128 v[156:159], v76 offset:1088
	ds_read_b128 v[160:163], v76 offset:1120
	ds_read_b128 v[164:167], v76 offset:1280
	ds_read_b128 v[168:171], v76 offset:1312
	ds_read_b128 v[172:175], v76 offset:1344
	ds_read_b128 v[176:179], v76 offset:1376
	ds_read_b128 v[192:195], v76 offset:1152
	ds_read_b128 v[196:199], v76 offset:1184
	ds_read_b128 v[200:203], v76 offset:1216
	ds_read_b128 v[204:207], v76 offset:1248
	ds_read_b128 v[208:211], v76 offset:1408
	ds_read_b128 v[212:215], v76 offset:1440
	ds_read_b128 v[216:219], v76 offset:1472
	ds_read_b128 v[220:223], v76 offset:1504
	s_waitcnt lgkmcnt(8)
	v_pk_mul_f32 v[64:65], v[0:1], v[148:149]
	v_pk_mul_f32 v[68:69], v[0:1], v[164:165]
	v_pk_fma_f32 v[64:65], v[2:3], v[150:151], v[64:65]
	v_pk_fma_f32 v[68:69], v[2:3], v[166:167], v[68:69]
	v_pk_fma_f32 v[64:65], v[4:5], v[152:153], v[64:65]
	v_pk_fma_f32 v[68:69], v[4:5], v[168:169], v[68:69]
	v_pk_fma_f32 v[64:65], v[6:7], v[154:155], v[64:65]
	v_pk_fma_f32 v[68:69], v[6:7], v[170:171], v[68:69]
	v_pk_fma_f32 v[64:65], v[8:9], v[156:157], v[64:65]
	v_pk_fma_f32 v[68:69], v[8:9], v[172:173], v[68:69]
	v_pk_fma_f32 v[64:65], v[10:11], v[158:159], v[64:65]
	v_pk_fma_f32 v[68:69], v[10:11], v[174:175], v[68:69]
	v_pk_fma_f32 v[64:65], v[12:13], v[160:161], v[64:65]
	v_pk_fma_f32 v[68:69], v[12:13], v[176:177], v[68:69]
	v_pk_fma_f32 v[64:65], v[14:15], v[162:163], v[64:65]
	v_pk_fma_f32 v[68:69], v[14:15], v[178:179], v[68:69]
	v_pk_mul_f32 v[66:67], v[32:33], v[148:149]
	v_pk_mul_f32 v[70:71], v[32:33], v[164:165]
	v_pk_fma_f32 v[66:67], v[34:35], v[150:151], v[66:67]
	v_pk_fma_f32 v[70:71], v[34:35], v[166:167], v[70:71]
	v_pk_fma_f32 v[66:67], v[36:37], v[152:153], v[66:67]
	v_pk_fma_f32 v[70:71], v[36:37], v[168:169], v[70:71]
	v_pk_fma_f32 v[66:67], v[38:39], v[154:155], v[66:67]
	v_pk_fma_f32 v[70:71], v[38:39], v[170:171], v[70:71]
	v_pk_fma_f32 v[66:67], v[40:41], v[156:157], v[66:67]
	v_pk_fma_f32 v[70:71], v[40:41], v[172:173], v[70:71]
	v_pk_fma_f32 v[66:67], v[42:43], v[158:159], v[66:67]
	v_pk_fma_f32 v[70:71], v[42:43], v[174:175], v[70:71]
	v_pk_fma_f32 v[66:67], v[44:45], v[160:161], v[66:67]
	v_pk_fma_f32 v[70:71], v[44:45], v[176:177], v[70:71]
	v_pk_fma_f32 v[66:67], v[46:47], v[162:163], v[66:67]
	v_pk_fma_f32 v[70:71], v[46:47], v[178:179], v[70:71]
	s_waitcnt lgkmcnt(0)
; __device__ __forceinline__ float bf2f(unsigned short b) { return __uint_as_float((unsigned)b << 16); }
; __device__ __forceinline__ f2 pfma(f2 a, f2 b, f2 c) { return __builtin_elementwise_fma(a, b, c); }
; template <bool ID> __device__ __forceinline__ void rwkv_scan(const bf16_t* __restrict__ R, const bf16_t* __restrict__ EW, const bf16_t* __restrict__ K, const bf16_t* __restrict__ V, ...
;     ...
;     { L[lane] = bf2f(q1[4]);
;       f2 av = {0.f, 0.f}, ai = {0.f, 0.f};
; #pragma unroll
;       for (int q = 0; q < 16; ++q) { const f32x4 a4 = pa[q]; const f2 a01 = {a4[0], a4[1]}, a23 = {a4[2], a4[3]};
;           av = pfma(Sv[2 * q], a01, av); av = pfma(Sv[2 * q + 1], a23, av); if (ID) { ai = pfma(Si[2 * q], a01, ai); ai = pfma(Si[2 * q + 1], a23, ai); } }
;       sav = av[0] + av[1]; sai = ai[0] + ai[1]; }
;     ...
;     for (int s = 0; s < nsteps; ++s) {
;         L[lane] = bf2f(q2[4]); L[64 + lane] = __expf(-bf2f(q1[1])); L[128 + lane] = bf2f(q1[5]); L[192 + lane] = bf2f(q1[2]); L[256 + lane] = bf2f(q1[0]);
;         const float v = bf2f(q1[3]);
; #pragma unroll
;         for (int j = 0; j < 6; ++j) q1[j] = q2[j];
;         { const unsigned o = base + (unsigned)(s + 2 < nsteps ? s + 2 : nsteps - 1) * 512u; q2[0] = R[o]; q2[1] = EW[o]; q2[2] = K[o]; q2[3] = V[o]; q2[4] = A[o]; q2[5] = B[o]; }
;         const f2 sav2 = {sav, sav}, sai2 = {sai, sai}, v2 = {v, v};
;         f2 yv = {0.f, 0.f}, yi = {0.f, 0.f}, yv1 = {0.f, 0.f}, yi1 = {0.f, 0.f}, nv = {0.f, 0.f}, ni = {0.f, 0.f}, nv1 = {0.f, 0.f}, ni1 = {0.f, 0.f};
;         f32x4 ca = pa[0], cw = pa[16], cb = pa[32], ck = pa[48], cr = pa[64];
; #pragma unroll
;         for (int q = 0; q < 16; ++q) {
;             const f32x4 a4 = ca, w4 = cw, b4 = cb, k4 = ck, r4 = cr;
;             if (q < 15) { ca = pa[1 + q]; cw = pa[17 + q]; cb = pa[33 + q]; ck = pa[49 + q]; cr = pa[65 + q]; }
;             __builtin_amdgcn_sched_barrier(0);
;             { const f2 a2 = {a4[0], a4[1]}, w2 = {w4[0], w4[1]}, b2 = {b4[0], b4[1]}, k2 = {k4[0], k4[1]}, r2 = {r4[0], r4[1]};
;               f2 tv = sav2 * b2; tv = pfma(v2, k2, tv); Sv[2 * q] = pfma(Sv[2 * q], w2, tv); yv = pfma(Sv[2 * q], r2, yv); nv = pfma(Sv[2 * q], a2, nv);
;               if (ID) { const f2 ti = sai2 * b2; Si[2 * q] = pfma(Si[2 * q], w2, ti); yi = pfma(Si[2 * q], r2, yi); ni = pfma(Si[2 * q], a2, ni); } }
	v_pk_fma_f32 v[64:65], v[16:17], v[192:193], v[64:65]
	v_pk_fma_f32 v[68:69], v[16:17], v[208:209], v[68:69]
	v_pk_fma_f32 v[64:65], v[18:19], v[194:195], v[64:65]
	v_pk_fma_f32 v[68:69], v[18:19], v[210:211], v[68:69]
	v_pk_fma_f32 v[64:65], v[20:21], v[196:197], v[64:65]
	v_pk_fma_f32 v[68:69], v[20:21], v[212:213], v[68:69]
	v_pk_fma_f32 v[64:65], v[22:23], v[198:199], v[64:65]
	v_pk_fma_f32 v[68:69], v[22:23], v[214:215], v[68:69]
	v_pk_fma_f32 v[64:65], v[24:25], v[200:201], v[64:65]
	v_pk_fma_f32 v[68:69], v[24:25], v[216:217], v[68:69]
	v_pk_fma_f32 v[64:65], v[26:27], v[202:203], v[64:65]
	v_pk_fma_f32 v[68:69], v[26:27], v[218:219], v[68:69]
	v_pk_fma_f32 v[64:65], v[28:29], v[204:205], v[64:65]
	v_pk_fma_f32 v[68:69], v[28:29], v[220:221], v[68:69]
	v_pk_fma_f32 v[64:65], v[30:31], v[206:207], v[64:65]
	v_pk_fma_f32 v[68:69], v[30:31], v[222:223], v[68:69]
	v_pk_fma_f32 v[66:67], v[48:49], v[192:193], v[66:67]
	v_pk_fma_f32 v[70:71], v[48:49], v[208:209], v[70:71]
	v_pk_fma_f32 v[66:67], v[50:51], v[194:195], v[66:67]
	v_pk_fma_f32 v[70:71], v[50:51], v[210:211], v[70:71]
	v_pk_fma_f32 v[66:67], v[52:53], v[196:197], v[66:67]
	v_pk_fma_f32 v[70:71], v[52:53], v[212:213], v[70:71]
	v_pk_fma_f32 v[66:67], v[54:55], v[198:199], v[66:67]
	v_pk_fma_f32 v[70:71], v[54:55], v[214:215], v[70:71]
	v_pk_fma_f32 v[66:67], v[56:57], v[200:201], v[66:67]
	v_pk_fma_f32 v[70:71], v[56:57], v[216:217], v[70:71]
	v_pk_fma_f32 v[66:67], v[58:59], v[202:203], v[66:67]
	v_pk_fma_f32 v[70:71], v[58:59], v[218:219], v[70:71]
	v_pk_fma_f32 v[66:67], v[60:61], v[204:205], v[66:67]
	v_pk_fma_f32 v[70:71], v[60:61], v[220:221], v[70:71]
	v_pk_fma_f32 v[66:67], v[62:63], v[206:207], v[66:67]
	v_pk_fma_f32 v[70:71], v[62:63], v[222:223], v[70:71]
	v_add_f32_e32 v68, v68, v69
	v_add_f32_e32 v70, v70, v71
	s_nop 0
	s_nop 0
	v_permlane32_swap_b32_e32 v68, v70
	v_add_f32_e32 v255, v68, v70
	v_lshlrev_b32_e32 v78, 16, v224
	v_mul_f32_e32 v78, 0xbfb8aa3b, v78
	v_exp_f32_e32 v78, v78
	v_lshlrev_b32_e32 v79, 16, v225
	v_lshlrev_b32_e32 v80, 16, v226
	v_mul_f32_e32 v246, v246, v78
	v_mul_f32_e32 v79, v79, v246
	v_mul_f32_e32 v80, v80, v246
	v_rcp_f32_e32 v248, v246
	s_nop 0
	ds_write2st64_b32 v77, v248, v79 offset0:0 offset1:1
	ds_write_b32 v77, v80 offset:512
	ds_read_b32 v249, v251 offset:0
	ds_read_b32 v250, v251 offset:128
	v_lshlrev_b32_e32 v240, 16, v227
	v_lshlrev_b32_e32 v241, 16, v228
	s_waitcnt lgkmcnt(0)
	v_mul_f32_e32 v240, v240, v249
	v_mul_f32_e32 v241, v241, v250
	v_mov_b32_e32 v244, v255
	v_lshlrev_b32_e32 v245, 16, v229
	s_nop 0
	s_nop 0
	v_permlane32_swap_b32_e32 v244, v245
	s_movk_i32 s41, 0
.Lscan_s_loop:
	ds_read_b128 v[192:195], v76 offset:256
	ds_read_b128 v[196:199], v76 offset:288
	ds_read_b128 v[200:203], v76 offset:320
	ds_read_b128 v[204:207], v76 offset:352
	ds_read_b128 v[208:211], v76 offset:512
	ds_read_b128 v[212:215], v76 offset:544
	ds_read_b128 v[216:219], v76 offset:576
	ds_read_b128 v[220:223], v76 offset:608
	global_load_ushort v224, v72, s[4:5] offset:0
	global_load_ushort v225, v72, s[0:1] offset:0
	global_load_ushort v226, v72, s[12:13] offset:1024
	global_load_ushort v227, v[74:75], off offset:0
	global_load_ushort v228, v[74:75], off offset:64
	global_load_ushort v229, v72, s[2:3] offset:0
	v_mfma_f32_32x32x2_f32 v[0:15], v240, v244, v[0:15]
	v_mfma_f32_32x32x2_f32 v[32:47], v240, v245, v[32:47]
	ds_read_b128 v[148:151], v76 offset:384
	ds_read_b128 v[152:155], v76 offset:416
	ds_read_b128 v[156:159], v76 offset:448
	ds_read_b128 v[160:163], v76 offset:480
	ds_read_b128 v[164:167], v76 offset:640
	ds_read_b128 v[168:171], v76 offset:672
	ds_read_b128 v[172:175], v76 offset:704
	ds_read_b128 v[176:179], v76 offset:736
	v_mfma_f32_32x32x2_f32 v[16:31], v241, v244, v[16:31]
	v_mfma_f32_32x32x2_f32 v[48:63], v241, v245, v[48:63]
	v_lshlrev_b32_e32 v78, 16, v230
	v_mul_f32_e32 v78, 0xbfb8aa3b, v78
	v_exp_f32_e32 v78, v78
	v_lshlrev_b32_e32 v79, 16, v231
	v_lshlrev_b32_e32 v80, 16, v232
	v_mul_f32_e32 v246, v246, v78
	v_mul_f32_e32 v79, v79, v246
	v_mul_f32_e32 v80, v80, v246
	v_rcp_f32_e32 v248, v246
	s_nop 0
	ds_write2st64_b32 v77, v248, v79 offset0:3 offset1:4
	ds_write_b32 v77, v80 offset:1280
	s_waitcnt lgkmcnt(10)
	v_pk_mul_f32 v[64:65], v[0:1], v[192:193]
	v_pk_mul_f32 v[68:69], v[0:1], v[208:209]
	v_pk_fma_f32 v[64:65], v[2:3], v[194:195], v[64:65]
	v_pk_fma_f32 v[68:69], v[2:3], v[210:211], v[68:69]
	v_pk_fma_f32 v[64:65], v[4:5], v[196:197], v[64:65]
	v_pk_fma_f32 v[68:69], v[4:5], v[212:213], v[68:69]
	v_pk_fma_f32 v[64:65], v[6:7], v[198:199], v[64:65]
	v_pk_fma_f32 v[68:69], v[6:7], v[214:215], v[68:69]
	v_pk_fma_f32 v[64:65], v[8:9], v[200:201], v[64:65]
	v_pk_fma_f32 v[68:69], v[8:9], v[216:217], v[68:69]
	v_pk_fma_f32 v[64:65], v[10:11], v[202:203], v[64:65]
	v_pk_fma_f32 v[68:69], v[10:11], v[218:219], v[68:69]
	v_pk_fma_f32 v[64:65], v[12:13], v[204:205], v[64:65]
	v_pk_fma_f32 v[68:69], v[12:13], v[220:221], v[68:69]
	v_pk_fma_f32 v[64:65], v[14:15], v[206:207], v[64:65]
	v_pk_fma_f32 v[68:69], v[14:15], v[222:223], v[68:69]
	v_pk_mul_f32 v[66:67], v[32:33], v[192:193]
	v_pk_mul_f32 v[70:71], v[32:33], v[208:209]
	v_pk_fma_f32 v[66:67], v[34:35], v[194:195], v[66:67]
	v_pk_fma_f32 v[70:71], v[34:35], v[210:211], v[70:71]
	v_pk_fma_f32 v[66:67], v[36:37], v[196:197], v[66:67]
	v_pk_fma_f32 v[70:71], v[36:37], v[212:213], v[70:71]
	v_pk_fma_f32 v[66:67], v[38:39], v[198:199], v[66:67]
	v_pk_fma_f32 v[70:71], v[38:39], v[214:215], v[70:71]
	v_pk_fma_f32 v[66:67], v[40:41], v[200:201], v[66:67]
	v_pk_fma_f32 v[70:71], v[40:41], v[216:217], v[70:71]
	v_pk_fma_f32 v[66:67], v[42:43], v[202:203], v[66:67]
	v_pk_fma_f32 v[70:71], v[42:43], v[218:219], v[70:71]
	v_pk_fma_f32 v[66:67], v[44:45], v[204:205], v[66:67]
	v_pk_fma_f32 v[70:71], v[44:45], v[220:221], v[70:71]
	v_pk_fma_f32 v[66:67], v[46:47], v[206:207], v[66:67]
	v_pk_fma_f32 v[70:71], v[46:47], v[222:223], v[70:71]
	s_waitcnt lgkmcnt(2)
; template <bool ID> __device__ __forceinline__ void rwkv_scan(const bf16_t* __restrict__ R, const bf16_t* __restrict__ EW, const bf16_t* __restrict__ K, const bf16_t* __restrict__ V, ...
;     ...
;         L[lane] = bf2f(q2[4]); L[64 + lane] = __expf(-bf2f(q1[1])); L[128 + lane] = bf2f(q1[5]); L[192 + lane] = bf2f(q1[2]); L[256 + lane] = bf2f(q1[0]);
;         const float v = bf2f(q1[3]);
; #pragma unroll
;         for (int j = 0; j < 6; ++j) q1[j] = q2[j];
;         { const unsigned o = base + (unsigned)(s + 2 < nsteps ? s + 2 : nsteps - 1) * 512u; q2[0] = R[o]; q2[1] = EW[o]; q2[2] = K[o]; q2[3] = V[o]; q2[4] = A[o]; q2[5] = B[o]; }
;         const f2 sav2 = {sav, sav}, sai2 = {sai, sai}, v2 = {v, v};
;         f2 yv = {0.f, 0.f}, yi = {0.f, 0.f}, yv1 = {0.f, 0.f}, yi1 = {0.f, 0.f}, nv = {0.f, 0.f}, ni = {0.f, 0.f}, nv1 = {0.f, 0.f}, ni1 = {0.f, 0.f};
;         f32x4 ca = pa[0], cw = pa[16], cb = pa[32], ck = pa[48], cr = pa[64];
; #pragma unroll
;         for (int q = 0; q < 16; ++q) {
;             const f32x4 a4 = ca, w4 = cw, b4 = cb, k4 = ck, r4 = cr;
;             if (q < 15) { ca = pa[1 + q]; cw = pa[17 + q]; cb = pa[33 + q]; ck = pa[49 + q]; cr = pa[65 + q]; }
;             __builtin_amdgcn_sched_barrier(0);
;             { const f2 a2 = {a4[0], a4[1]}, w2 = {w4[0], w4[1]}, b2 = {b4[0], b4[1]}, k2 = {k4[0], k4[1]}, r2 = {r4[0], r4[1]};
;               f2 tv = sav2 * b2; tv = pfma(v2, k2, tv); Sv[2 * q] = pfma(Sv[2 * q], w2, tv); yv = pfma(Sv[2 * q], r2, yv); nv = pfma(Sv[2 * q], a2, nv);
;               if (ID) { const f2 ti = sai2 * b2; Si[2 * q] = pfma(Si[2 * q], w2, ti); yi = pfma(Si[2 * q], r2, yi); ni = pfma(Si[2 * q], a2, ni); } }
;             { const f2 a2 = {a4[2], a4[3]}, w2 = {w4[2], w4[3]}, b2 = {b4[2], b4[3]}, k2 = {k4[2], k4[3]}, r2 = {r4[2], r4[3]};
;               f2 tv = sav2 * b2; tv = pfma(v2, k2, tv); Sv[2 * q + 1] = pfma(Sv[2 * q + 1], w2, tv); yv1 = pfma(Sv[2 * q + 1], r2, yv1); nv1 = pfma(Sv[2 * q + 1], a2, nv1);
;               if (ID) { const f2 ti = sai2 * b2; Si[2 * q + 1] = pfma(Si[2 * q + 1], w2, ti); yi1 = pfma(Si[2 * q + 1], r2, yi1); ni1 = pfma(Si[2 * q + 1], a2, ni1); } }
;         }
;         sav = (nv[0] + nv[1]) + (nv1[0] + nv1[1]); sai = (ni[0] + ni[1]) + (ni1[0] + ni1[1]);
;         const unsigned cbo = base + (unsigned)s * 512u;
	v_pk_fma_f32 v[64:65], v[16:17], v[148:149], v[64:65]
	v_pk_fma_f32 v[68:69], v[16:17], v[164:165], v[68:69]
	v_pk_fma_f32 v[64:65], v[18:19], v[150:151], v[64:65]
	v_pk_fma_f32 v[68:69], v[18:19], v[166:167], v[68:69]
	v_pk_fma_f32 v[64:65], v[20:21], v[152:153], v[64:65]
	v_pk_fma_f32 v[68:69], v[20:21], v[168:169], v[68:69]
	v_pk_fma_f32 v[64:65], v[22:23], v[154:155], v[64:65]
	v_pk_fma_f32 v[68:69], v[22:23], v[170:171], v[68:69]
	v_pk_fma_f32 v[64:65], v[24:25], v[156:157], v[64:65]
	v_pk_fma_f32 v[68:69], v[24:25], v[172:173], v[68:69]
	v_pk_fma_f32 v[64:65], v[26:27], v[158:159], v[64:65]
	v_pk_fma_f32 v[68:69], v[26:27], v[174:175], v[68:69]
	v_pk_fma_f32 v[64:65], v[28:29], v[160:161], v[64:65]
	v_pk_fma_f32 v[68:69], v[28:29], v[176:177], v[68:69]
	v_pk_fma_f32 v[64:65], v[30:31], v[162:163], v[64:65]
	v_pk_fma_f32 v[68:69], v[30:31], v[178:179], v[68:69]
	v_pk_fma_f32 v[66:67], v[48:49], v[148:149], v[66:67]
	v_pk_fma_f32 v[70:71], v[48:49], v[164:165], v[70:71]
	v_pk_fma_f32 v[66:67], v[50:51], v[150:151], v[66:67]
	v_pk_fma_f32 v[70:71], v[50:51], v[166:167], v[70:71]
	v_pk_fma_f32 v[66:67], v[52:53], v[152:153], v[66:67]
	v_pk_fma_f32 v[70:71], v[52:53], v[168:169], v[70:71]
	v_pk_fma_f32 v[66:67], v[54:55], v[154:155], v[66:67]
	v_pk_fma_f32 v[70:71], v[54:55], v[170:171], v[70:71]
	v_pk_fma_f32 v[66:67], v[56:57], v[156:157], v[66:67]
	v_pk_fma_f32 v[70:71], v[56:57], v[172:173], v[70:71]
	v_pk_fma_f32 v[66:67], v[58:59], v[158:159], v[66:67]
	v_pk_fma_f32 v[70:71], v[58:59], v[174:175], v[70:71]
	v_pk_fma_f32 v[66:67], v[60:61], v[160:161], v[66:67]
	v_pk_fma_f32 v[70:71], v[60:61], v[176:177], v[70:71]
	v_pk_fma_f32 v[66:67], v[62:63], v[162:163], v[66:67]
	v_pk_fma_f32 v[70:71], v[62:63], v[178:179], v[70:71]
	ds_read_b32 v249, v251 offset:768
	ds_read_b32 v250, v251 offset:896
	v_lshlrev_b32_e32 v240, 16, v233
	v_lshlrev_b32_e32 v241, 16, v234
	s_waitcnt lgkmcnt(0)
	v_mul_f32_e32 v240, v240, v249
	v_mul_f32_e32 v241, v241, v250
	v_add_f32_e32 v68, v68, v69
	v_add_f32_e32 v70, v70, v71
	v_add_f32_e32 v64, v64, v65
	v_add_f32_e32 v66, v66, v67
	v_lshlrev_b32_e32 v245, 16, v235
	v_permlane32_swap_b32_e32 v68, v70
	v_permlane32_swap_b32_e32 v64, v66
	v_add_f32_e32 v244, v68, v70
	v_add_f32_e32 v64, v64, v66
	v_bfe_u32 v66, v64, 16, 1
	v_add3_u32 v66, v64, v66, s69
	v_permlane32_swap_b32_e32 v244, v245
	global_store_short_d16_hi v72, v66, s[22:23] offset:-4096
	v_add_u32_e32 v72, 0x400, v72
	v_lshl_add_u64 v[74:75], v[74:75], 0, s[54:55]
	ds_read_b128 v[148:151], v76 offset:1024
	ds_read_b128 v[152:155], v76 offset:1056
	ds_read_b128 v[156:159], v76 offset:1088
	ds_read_b128 v[160:163], v76 offset:1120
	ds_read_b128 v[164:167], v76 offset:1280
	ds_read_b128 v[168:171], v76 offset:1312
	ds_read_b128 v[172:175], v76 offset:1344
	ds_read_b128 v[176:179], v76 offset:1376
	global_load_ushort v230, v72, s[4:5] offset:0
	global_load_ushort v231, v72, s[0:1] offset:0
	global_load_ushort v232, v72, s[12:13] offset:1024
	global_load_ushort v233, v[74:75], off offset:0
	global_load_ushort v234, v[74:75], off offset:64
	global_load_ushort v235, v72, s[2:3] offset:0
	v_mfma_f32_32x32x2_f32 v[0:15], v240, v244, v[0:15]
	v_mfma_f32_32x32x2_f32 v[32:47], v240, v245, v[32:47]
	ds_read_b128 v[192:195], v76 offset:1152
	ds_read_b128 v[196:199], v76 offset:1184
	ds_read_b128 v[200:203], v76 offset:1216
	ds_read_b128 v[204:207], v76 offset:1248
	ds_read_b128 v[208:211], v76 offset:1408
	ds_read_b128 v[212:215], v76 offset:1440
	ds_read_b128 v[216:219], v76 offset:1472
	ds_read_b128 v[220:223], v76 offset:1504
	v_mfma_f32_32x32x2_f32 v[16:31], v241, v244, v[16:31]
	v_mfma_f32_32x32x2_f32 v[48:63], v241, v245, v[48:63]
	v_lshlrev_b32_e32 v78, 16, v82
	v_mul_f32_e32 v78, 0xbfb8aa3b, v78
	v_exp_f32_e32 v78, v78
	v_lshlrev_b32_e32 v79, 16, v83
	v_lshlrev_b32_e32 v80, 16, v84
	v_mul_f32_e32 v246, v246, v78
	v_mul_f32_e32 v79, v79, v246
	v_mul_f32_e32 v80, v80, v246
	v_rcp_f32_e32 v248, v246
	s_nop 0
	ds_write2st64_b32 v77, v248, v79 offset0:0 offset1:1
	ds_write_b32 v77, v80 offset:512
	s_waitcnt lgkmcnt(10)
	v_pk_mul_f32 v[64:65], v[0:1], v[148:149]
	v_pk_mul_f32 v[68:69], v[0:1], v[164:165]
	v_pk_fma_f32 v[64:65], v[2:3], v[150:151], v[64:65]
	v_pk_fma_f32 v[68:69], v[2:3], v[166:167], v[68:69]
	v_pk_fma_f32 v[64:65], v[4:5], v[152:153], v[64:65]
	v_pk_fma_f32 v[68:69], v[4:5], v[168:169], v[68:69]
	v_pk_fma_f32 v[64:65], v[6:7], v[154:155], v[64:65]
	v_pk_fma_f32 v[68:69], v[6:7], v[170:171], v[68:69]
	v_pk_fma_f32 v[64:65], v[8:9], v[156:157], v[64:65]
	v_pk_fma_f32 v[68:69], v[8:9], v[172:173], v[68:69]
	v_pk_fma_f32 v[64:65], v[10:11], v[158:159], v[64:65]
	v_pk_fma_f32 v[68:69], v[10:11], v[174:175], v[68:69]
	v_pk_fma_f32 v[64:65], v[12:13], v[160:161], v[64:65]
	v_pk_fma_f32 v[68:69], v[12:13], v[176:177], v[68:69]
	v_pk_fma_f32 v[64:65], v[14:15], v[162:163], v[64:65]
	v_pk_fma_f32 v[68:69], v[14:15], v[178:179], v[68:69]
	v_pk_mul_f32 v[66:67], v[32:33], v[148:149]
	v_pk_mul_f32 v[70:71], v[32:33], v[164:165]
	v_pk_fma_f32 v[66:67], v[34:35], v[150:151], v[66:67]
	v_pk_fma_f32 v[70:71], v[34:35], v[166:167], v[70:71]
	v_pk_fma_f32 v[66:67], v[36:37], v[152:153], v[66:67]
	v_pk_fma_f32 v[70:71], v[36:37], v[168:169], v[70:71]
	v_pk_fma_f32 v[66:67], v[38:39], v[154:155], v[66:67]
	v_pk_fma_f32 v[70:71], v[38:39], v[170:171], v[70:71]
	v_pk_fma_f32 v[66:67], v[40:41], v[156:157], v[66:67]
	v_pk_fma_f32 v[70:71], v[40:41], v[172:173], v[70:71]
	v_pk_fma_f32 v[66:67], v[42:43], v[158:159], v[66:67]
	v_pk_fma_f32 v[70:71], v[42:43], v[174:175], v[70:71]
	v_pk_fma_f32 v[66:67], v[44:45], v[160:161], v[66:67]
	v_pk_fma_f32 v[70:71], v[44:45], v[176:177], v[70:71]
	v_pk_fma_f32 v[66:67], v[46:47], v[162:163], v[66:67]
	v_pk_fma_f32 v[70:71], v[46:47], v[178:179], v[70:71]
	s_waitcnt lgkmcnt(2)
; template <bool ID> __device__ __forceinline__ void rwkv_scan(const bf16_t* __restrict__ R, const bf16_t* __restrict__ EW, const bf16_t* __restrict__ K, const bf16_t* __restrict__ V, ...
;     ...
;         L[lane] = bf2f(q2[4]); L[64 + lane] = __expf(-bf2f(q1[1])); L[128 + lane] = bf2f(q1[5]); L[192 + lane] = bf2f(q1[2]); L[256 + lane] = bf2f(q1[0]);
;         const float v = bf2f(q1[3]);
; #pragma unroll
;         for (int j = 0; j < 6; ++j) q1[j] = q2[j];
;         { const unsigned o = base + (unsigned)(s + 2 < nsteps ? s + 2 : nsteps - 1) * 512u; q2[0] = R[o]; q2[1] = EW[o]; q2[2] = K[o]; q2[3] = V[o]; q2[4] = A[o]; q2[5] = B[o]; }
;         const f2 sav2 = {sav, sav}, sai2 = {sai, sai}, v2 = {v, v};
;         f2 yv = {0.f, 0.f}, yi = {0.f, 0.f}, yv1 = {0.f, 0.f}, yi1 = {0.f, 0.f}, nv = {0.f, 0.f}, ni = {0.f, 0.f}, nv1 = {0.f, 0.f}, ni1 = {0.f, 0.f};
;         f32x4 ca = pa[0], cw = pa[16], cb = pa[32], ck = pa[48], cr = pa[64];
; #pragma unroll
;         for (int q = 0; q < 16; ++q) {
;             const f32x4 a4 = ca, w4 = cw, b4 = cb, k4 = ck, r4 = cr;
;             if (q < 15) { ca = pa[1 + q]; cw = pa[17 + q]; cb = pa[33 + q]; ck = pa[49 + q]; cr = pa[65 + q]; }
;             __builtin_amdgcn_sched_barrier(0);
;             { const f2 a2 = {a4[0], a4[1]}, w2 = {w4[0], w4[1]}, b2 = {b4[0], b4[1]}, k2 = {k4[0], k4[1]}, r2 = {r4[0], r4[1]};
;               f2 tv = sav2 * b2; tv = pfma(v2, k2, tv); Sv[2 * q] = pfma(Sv[2 * q], w2, tv); yv = pfma(Sv[2 * q], r2, yv); nv = pfma(Sv[2 * q], a2, nv);
;               if (ID) { const f2 ti = sai2 * b2; Si[2 * q] = pfma(Si[2 * q], w2, ti); yi = pfma(Si[2 * q], r2, yi); ni = pfma(Si[2 * q], a2, ni); } }
;             { const f2 a2 = {a4[2], a4[3]}, w2 = {w4[2], w4[3]}, b2 = {b4[2], b4[3]}, k2 = {k4[2], k4[3]}, r2 = {r4[2], r4[3]};
;               f2 tv = sav2 * b2; tv = pfma(v2, k2, tv); Sv[2 * q + 1] = pfma(Sv[2 * q + 1], w2, tv); yv1 = pfma(Sv[2 * q + 1], r2, yv1); nv1 = pfma(Sv[2 * q + 1], a2, nv1);
;               if (ID) { const f2 ti = sai2 * b2; Si[2 * q + 1] = pfma(Si[2 * q + 1], w2, ti); yi1 = pfma(Si[2 * q + 1], r2, yi1); ni1 = pfma(Si[2 * q + 1], a2, ni1); } }
;         }
;         sav = (nv[0] + nv[1]) + (nv1[0] + nv1[1]); sai = (ni[0] + ni[1]) + (ni1[0] + ni1[1]);
;         const unsigned cbo = base + (unsigned)s * 512u;
	v_pk_fma_f32 v[64:65], v[16:17], v[192:193], v[64:65]
	v_pk_fma_f32 v[68:69], v[16:17], v[208:209], v[68:69]
	v_pk_fma_f32 v[64:65], v[18:19], v[194:195], v[64:65]
	v_pk_fma_f32 v[68:69], v[18:19], v[210:211], v[68:69]
	v_pk_fma_f32 v[64:65], v[20:21], v[196:197], v[64:65]
	v_pk_fma_f32 v[68:69], v[20:21], v[212:213], v[68:69]
	v_pk_fma_f32 v[64:65], v[22:23], v[198:199], v[64:65]
	v_pk_fma_f32 v[68:69], v[22:23], v[214:215], v[68:69]
	v_pk_fma_f32 v[64:65], v[24:25], v[200:201], v[64:65]
	v_pk_fma_f32 v[68:69], v[24:25], v[216:217], v[68:69]
	v_pk_fma_f32 v[64:65], v[26:27], v[202:203], v[64:65]
	v_pk_fma_f32 v[68:69], v[26:27], v[218:219], v[68:69]
	v_pk_fma_f32 v[64:65], v[28:29], v[204:205], v[64:65]
	v_pk_fma_f32 v[68:69], v[28:29], v[220:221], v[68:69]
	v_pk_fma_f32 v[64:65], v[30:31], v[206:207], v[64:65]
	v_pk_fma_f32 v[68:69], v[30:31], v[222:223], v[68:69]
	v_pk_fma_f32 v[66:67], v[48:49], v[192:193], v[66:67]
	v_pk_fma_f32 v[70:71], v[48:49], v[208:209], v[70:71]
	v_pk_fma_f32 v[66:67], v[50:51], v[194:195], v[66:67]
	v_pk_fma_f32 v[70:71], v[50:51], v[210:211], v[70:71]
	v_pk_fma_f32 v[66:67], v[52:53], v[196:197], v[66:67]
	v_pk_fma_f32 v[70:71], v[52:53], v[212:213], v[70:71]
	v_pk_fma_f32 v[66:67], v[54:55], v[198:199], v[66:67]
	v_pk_fma_f32 v[70:71], v[54:55], v[214:215], v[70:71]
	v_pk_fma_f32 v[66:67], v[56:57], v[200:201], v[66:67]
	v_pk_fma_f32 v[70:71], v[56:57], v[216:217], v[70:71]
	v_pk_fma_f32 v[66:67], v[58:59], v[202:203], v[66:67]
	v_pk_fma_f32 v[70:71], v[58:59], v[218:219], v[70:71]
	v_pk_fma_f32 v[66:67], v[60:61], v[204:205], v[66:67]
	v_pk_fma_f32 v[70:71], v[60:61], v[220:221], v[70:71]
	v_pk_fma_f32 v[66:67], v[62:63], v[206:207], v[66:67]
	v_pk_fma_f32 v[70:71], v[62:63], v[222:223], v[70:71]
	ds_read_b32 v249, v251 offset:0
	ds_read_b32 v250, v251 offset:128
	v_lshlrev_b32_e32 v240, 16, v85
	v_lshlrev_b32_e32 v241, 16, v86
	s_waitcnt lgkmcnt(0)
	v_mul_f32_e32 v240, v240, v249
	v_mul_f32_e32 v241, v241, v250
	v_add_f32_e32 v68, v68, v69
	v_add_f32_e32 v70, v70, v71
	v_add_f32_e32 v64, v64, v65
	v_add_f32_e32 v66, v66, v67
	v_lshlrev_b32_e32 v245, 16, v87
	v_permlane32_swap_b32_e32 v68, v70
	v_permlane32_swap_b32_e32 v64, v66
	v_add_f32_e32 v244, v68, v70
	v_add_f32_e32 v64, v64, v66
	v_bfe_u32 v66, v64, 16, 1
	v_add3_u32 v66, v64, v66, s69
	v_permlane32_swap_b32_e32 v244, v245
	global_store_short_d16_hi v72, v66, s[22:23] offset:-4096
	v_add_u32_e32 v72, 0x400, v72
	v_lshl_add_u64 v[74:75], v[74:75], 0, s[54:55]
	ds_read_b128 v[192:195], v76 offset:256
	ds_read_b128 v[196:199], v76 offset:288
	ds_read_b128 v[200:203], v76 offset:320
	ds_read_b128 v[204:207], v76 offset:352
	ds_read_b128 v[208:211], v76 offset:512
	ds_read_b128 v[212:215], v76 offset:544
	ds_read_b128 v[216:219], v76 offset:576
	ds_read_b128 v[220:223], v76 offset:608
	global_load_ushort v82, v72, s[4:5] offset:0
	global_load_ushort v83, v72, s[0:1] offset:0
	global_load_ushort v84, v72, s[12:13] offset:1024
	global_load_ushort v85, v[74:75], off offset:0
	global_load_ushort v86, v[74:75], off offset:64
	global_load_ushort v87, v72, s[2:3] offset:0
	v_mfma_f32_32x32x2_f32 v[0:15], v240, v244, v[0:15]
	v_mfma_f32_32x32x2_f32 v[32:47], v240, v245, v[32:47]
	ds_read_b128 v[148:151], v76 offset:384
	ds_read_b128 v[152:155], v76 offset:416
	ds_read_b128 v[156:159], v76 offset:448
	ds_read_b128 v[160:163], v76 offset:480
	ds_read_b128 v[164:167], v76 offset:640
	ds_read_b128 v[168:171], v76 offset:672
	ds_read_b128 v[172:175], v76 offset:704
	ds_read_b128 v[176:179], v76 offset:736
	v_mfma_f32_32x32x2_f32 v[16:31], v241, v244, v[16:31]
	v_mfma_f32_32x32x2_f32 v[48:63], v241, v245, v[48:63]
	v_lshlrev_b32_e32 v78, 16, v88
	v_mul_f32_e32 v78, 0xbfb8aa3b, v78
	v_exp_f32_e32 v78, v78
	v_lshlrev_b32_e32 v79, 16, v89
	v_lshlrev_b32_e32 v80, 16, v90
	v_mul_f32_e32 v246, v246, v78
	v_mul_f32_e32 v79, v79, v246
	v_mul_f32_e32 v80, v80, v246
	v_rcp_f32_e32 v248, v246
	s_nop 0
	ds_write2st64_b32 v77, v248, v79 offset0:3 offset1:4
	ds_write_b32 v77, v80 offset:1280
	s_waitcnt lgkmcnt(10)
	v_pk_mul_f32 v[64:65], v[0:1], v[192:193]
	v_pk_mul_f32 v[68:69], v[0:1], v[208:209]
	v_pk_fma_f32 v[64:65], v[2:3], v[194:195], v[64:65]
	v_pk_fma_f32 v[68:69], v[2:3], v[210:211], v[68:69]
	v_pk_fma_f32 v[64:65], v[4:5], v[196:197], v[64:65]
	v_pk_fma_f32 v[68:69], v[4:5], v[212:213], v[68:69]
	v_pk_fma_f32 v[64:65], v[6:7], v[198:199], v[64:65]
	v_pk_fma_f32 v[68:69], v[6:7], v[214:215], v[68:69]
	v_pk_fma_f32 v[64:65], v[8:9], v[200:201], v[64:65]
	v_pk_fma_f32 v[68:69], v[8:9], v[216:217], v[68:69]
	v_pk_fma_f32 v[64:65], v[10:11], v[202:203], v[64:65]
	v_pk_fma_f32 v[68:69], v[10:11], v[218:219], v[68:69]
	v_pk_fma_f32 v[64:65], v[12:13], v[204:205], v[64:65]
	v_pk_fma_f32 v[68:69], v[12:13], v[220:221], v[68:69]
	v_pk_fma_f32 v[64:65], v[14:15], v[206:207], v[64:65]
	v_pk_fma_f32 v[68:69], v[14:15], v[222:223], v[68:69]
	v_pk_mul_f32 v[66:67], v[32:33], v[192:193]
	v_pk_mul_f32 v[70:71], v[32:33], v[208:209]
	v_pk_fma_f32 v[66:67], v[34:35], v[194:195], v[66:67]
	v_pk_fma_f32 v[70:71], v[34:35], v[210:211], v[70:71]
	v_pk_fma_f32 v[66:67], v[36:37], v[196:197], v[66:67]
	v_pk_fma_f32 v[70:71], v[36:37], v[212:213], v[70:71]
	v_pk_fma_f32 v[66:67], v[38:39], v[198:199], v[66:67]
	v_pk_fma_f32 v[70:71], v[38:39], v[214:215], v[70:71]
	v_pk_fma_f32 v[66:67], v[40:41], v[200:201], v[66:67]
	v_pk_fma_f32 v[70:71], v[40:41], v[216:217], v[70:71]
	v_pk_fma_f32 v[66:67], v[42:43], v[202:203], v[66:67]
	v_pk_fma_f32 v[70:71], v[42:43], v[218:219], v[70:71]
	v_pk_fma_f32 v[66:67], v[44:45], v[204:205], v[66:67]
	v_pk_fma_f32 v[70:71], v[44:45], v[220:221], v[70:71]
	v_pk_fma_f32 v[66:67], v[46:47], v[206:207], v[66:67]
	v_pk_fma_f32 v[70:71], v[46:47], v[222:223], v[70:71]
	s_waitcnt lgkmcnt(2)
; template <bool ID> __device__ __forceinline__ void rwkv_scan(const bf16_t* __restrict__ R, const bf16_t* __restrict__ EW, const bf16_t* __restrict__ K, const bf16_t* __restrict__ V, ...
;     ...
;         L[lane] = bf2f(q2[4]); L[64 + lane] = __expf(-bf2f(q1[1])); L[128 + lane] = bf2f(q1[5]); L[192 + lane] = bf2f(q1[2]); L[256 + lane] = bf2f(q1[0]);
;         const float v = bf2f(q1[3]);
; #pragma unroll
;         for (int j = 0; j < 6; ++j) q1[j] = q2[j];
;         { const unsigned o = base + (unsigned)(s + 2 < nsteps ? s + 2 : nsteps - 1) * 512u; q2[0] = R[o]; q2[1] = EW[o]; q2[2] = K[o]; q2[3] = V[o]; q2[4] = A[o]; q2[5] = B[o]; }
;         const f2 sav2 = {sav, sav}, sai2 = {sai, sai}, v2 = {v, v};
;         f2 yv = {0.f, 0.f}, yi = {0.f, 0.f}, yv1 = {0.f, 0.f}, yi1 = {0.f, 0.f}, nv = {0.f, 0.f}, ni = {0.f, 0.f}, nv1 = {0.f, 0.f}, ni1 = {0.f, 0.f};
;         f32x4 ca = pa[0], cw = pa[16], cb = pa[32], ck = pa[48], cr = pa[64];
; #pragma unroll
;         for (int q = 0; q < 16; ++q) {
;             const f32x4 a4 = ca, w4 = cw, b4 = cb, k4 = ck, r4 = cr;
;             if (q < 15) { ca = pa[1 + q]; cw = pa[17 + q]; cb = pa[33 + q]; ck = pa[49 + q]; cr = pa[65 + q]; }
;             __builtin_amdgcn_sched_barrier(0);
;             { const f2 a2 = {a4[0], a4[1]}, w2 = {w4[0], w4[1]}, b2 = {b4[0], b4[1]}, k2 = {k4[0], k4[1]}, r2 = {r4[0], r4[1]};
;               f2 tv = sav2 * b2; tv = pfma(v2, k2, tv); Sv[2 * q] = pfma(Sv[2 * q], w2, tv); yv = pfma(Sv[2 * q], r2, yv); nv = pfma(Sv[2 * q], a2, nv);
;               if (ID) { const f2 ti = sai2 * b2; Si[2 * q] = pfma(Si[2 * q], w2, ti); yi = pfma(Si[2 * q], r2, yi); ni = pfma(Si[2 * q], a2, ni); } }
;             { const f2 a2 = {a4[2], a4[3]}, w2 = {w4[2], w4[3]}, b2 = {b4[2], b4[3]}, k2 = {k4[2], k4[3]}, r2 = {r4[2], r4[3]};
;               f2 tv = sav2 * b2; tv = pfma(v2, k2, tv); Sv[2 * q + 1] = pfma(Sv[2 * q + 1], w2, tv); yv1 = pfma(Sv[2 * q + 1], r2, yv1); nv1 = pfma(Sv[2 * q + 1], a2, nv1);
;               if (ID) { const f2 ti = sai2 * b2; Si[2 * q + 1] = pfma(Si[2 * q + 1], w2, ti); yi1 = pfma(Si[2 * q + 1], r2, yi1); ni1 = pfma(Si[2 * q + 1], a2, ni1); } }
;         }
;         sav = (nv[0] + nv[1]) + (nv1[0] + nv1[1]); sai = (ni[0] + ni[1]) + (ni1[0] + ni1[1]);
;         const unsigned cbo = base + (unsigned)s * 512u;
	v_pk_fma_f32 v[64:65], v[16:17], v[148:149], v[64:65]
	v_pk_fma_f32 v[68:69], v[16:17], v[164:165], v[68:69]
	v_pk_fma_f32 v[64:65], v[18:19], v[150:151], v[64:65]
	v_pk_fma_f32 v[68:69], v[18:19], v[166:167], v[68:69]
	v_pk_fma_f32 v[64:65], v[20:21], v[152:153], v[64:65]
	v_pk_fma_f32 v[68:69], v[20:21], v[168:169], v[68:69]
	v_pk_fma_f32 v[64:65], v[22:23], v[154:155], v[64:65]
	v_pk_fma_f32 v[68:69], v[22:23], v[170:171], v[68:69]
	v_pk_fma_f32 v[64:65], v[24:25], v[156:157], v[64:65]
	v_pk_fma_f32 v[68:69], v[24:25], v[172:173], v[68:69]
	v_pk_fma_f32 v[64:65], v[26:27], v[158:159], v[64:65]
	v_pk_fma_f32 v[68:69], v[26:27], v[174:175], v[68:69]
	v_pk_fma_f32 v[64:65], v[28:29], v[160:161], v[64:65]
	v_pk_fma_f32 v[68:69], v[28:29], v[176:177], v[68:69]
	v_pk_fma_f32 v[64:65], v[30:31], v[162:163], v[64:65]
	v_pk_fma_f32 v[68:69], v[30:31], v[178:179], v[68:69]
	v_pk_fma_f32 v[66:67], v[48:49], v[148:149], v[66:67]
	v_pk_fma_f32 v[70:71], v[48:49], v[164:165], v[70:71]
	v_pk_fma_f32 v[66:67], v[50:51], v[150:151], v[66:67]
	v_pk_fma_f32 v[70:71], v[50:51], v[166:167], v[70:71]
	v_pk_fma_f32 v[66:67], v[52:53], v[152:153], v[66:67]
	v_pk_fma_f32 v[70:71], v[52:53], v[168:169], v[70:71]
	v_pk_fma_f32 v[66:67], v[54:55], v[154:155], v[66:67]
	v_pk_fma_f32 v[70:71], v[54:55], v[170:171], v[70:71]
	v_pk_fma_f32 v[66:67], v[56:57], v[156:157], v[66:67]
	v_pk_fma_f32 v[70:71], v[56:57], v[172:173], v[70:71]
	v_pk_fma_f32 v[66:67], v[58:59], v[158:159], v[66:67]
	v_pk_fma_f32 v[70:71], v[58:59], v[174:175], v[70:71]
	v_pk_fma_f32 v[66:67], v[60:61], v[160:161], v[66:67]
	v_pk_fma_f32 v[70:71], v[60:61], v[176:177], v[70:71]
	v_pk_fma_f32 v[66:67], v[62:63], v[162:163], v[66:67]
	v_pk_fma_f32 v[70:71], v[62:63], v[178:179], v[70:71]
	ds_read_b32 v249, v251 offset:768
	ds_read_b32 v250, v251 offset:896
	v_lshlrev_b32_e32 v240, 16, v91
	v_lshlrev_b32_e32 v241, 16, v92
	s_waitcnt lgkmcnt(0)
	v_mul_f32_e32 v240, v240, v249
	v_mul_f32_e32 v241, v241, v250
	v_add_f32_e32 v68, v68, v69
	v_add_f32_e32 v70, v70, v71
	v_add_f32_e32 v64, v64, v65
	v_add_f32_e32 v66, v66, v67
	v_lshlrev_b32_e32 v245, 16, v93
	v_permlane32_swap_b32_e32 v68, v70
	v_permlane32_swap_b32_e32 v64, v66
	v_add_f32_e32 v244, v68, v70
	v_add_f32_e32 v64, v64, v66
	v_bfe_u32 v66, v64, 16, 1
	v_add3_u32 v66, v64, v66, s69
	v_permlane32_swap_b32_e32 v244, v245
	global_store_short_d16_hi v72, v66, s[22:23] offset:-4096
	v_add_u32_e32 v72, 0x400, v72
	v_lshl_add_u64 v[74:75], v[74:75], 0, s[54:55]
	s_and_b32 s14, s41, 7
	s_cmp_eq_u32 s14, 7
	s_cbranch_scc1 .Lscan_s_s3x
; template <bool ID> __device__ __forceinline__ void rwkv_scan(const bf16_t* __restrict__ R, const bf16_t* __restrict__ EW, const bf16_t* __restrict__ K, const bf16_t* __restrict__ V, ...
;     ...
;     for (int s = 0; s < nsteps; ++s) {
;         L[lane] = bf2f(q2[4]); L[64 + lane] = __expf(-bf2f(q1[1])); L[128 + lane] = bf2f(q1[5]); L[192 + lane] = bf2f(q1[2]); L[256 + lane] = bf2f(q1[0]);
;         const float v = bf2f(q1[3]);
; #pragma unroll
;         for (int j = 0; j < 6; ++j) q1[j] = q2[j];
;         { const unsigned o = base + (unsigned)(s + 2 < nsteps ? s + 2 : nsteps - 1) * 512u; q2[0] = R[o]; q2[1] = EW[o]; q2[2] = K[o]; q2[3] = V[o]; q2[4] = A[o]; q2[5] = B[o]; }
;         const f2 sav2 = {sav, sav}, sai2 = {sai, sai}, v2 = {v, v};
;         f2 yv = {0.f, 0.f}, yi = {0.f, 0.f}, yv1 = {0.f, 0.f}, yi1 = {0.f, 0.f}, nv = {0.f, 0.f}, ni = {0.f, 0.f}, nv1 = {0.f, 0.f}, ni1 = {0.f, 0.f};
;         f32x4 ca = pa[0], cw = pa[16], cb = pa[32], ck = pa[48], cr = pa[64];
; #pragma unroll
;         for (int q = 0; q < 16; ++q) {
;             const f32x4 a4 = ca, w4 = cw, b4 = cb, k4 = ck, r4 = cr;
;             if (q < 15) { ca = pa[1 + q]; cw = pa[17 + q]; cb = pa[33 + q]; ck = pa[49 + q]; cr = pa[65 + q]; }
;             __builtin_amdgcn_sched_barrier(0);
;             { const f2 a2 = {a4[0], a4[1]}, w2 = {w4[0], w4[1]}, b2 = {b4[0], b4[1]}, k2 = {k4[0], k4[1]}, r2 = {r4[0], r4[1]};
;               f2 tv = sav2 * b2; tv = pfma(v2, k2, tv); Sv[2 * q] = pfma(Sv[2 * q], w2, tv); yv = pfma(Sv[2 * q], r2, yv); nv = pfma(Sv[2 * q], a2, nv);
;               if (ID) { const f2 ti = sai2 * b2; Si[2 * q] = pfma(Si[2 * q], w2, ti); yi = pfma(Si[2 * q], r2, yi); ni = pfma(Si[2 * q], a2, ni); } }
;             { const f2 a2 = {a4[2], a4[3]}, w2 = {w4[2], w4[3]}, b2 = {b4[2], b4[3]}, k2 = {k4[2], k4[3]}, r2 = {r4[2], r4[3]};
;               f2 tv = sav2 * b2; tv = pfma(v2, k2, tv); Sv[2 * q + 1] = pfma(Sv[2 * q + 1], w2, tv); yv1 = pfma(Sv[2 * q + 1], r2, yv1); nv1 = pfma(Sv[2 * q + 1], a2, nv1);
;               if (ID) { const f2 ti = sai2 * b2; Si[2 * q + 1] = pfma(Si[2 * q + 1], w2, ti); yi1 = pfma(Si[2 * q + 1], r2, yi1); ni1 = pfma(Si[2 * q + 1], a2, ni1); } }
;         }
;         sav = (nv[0] + nv[1]) + (nv1[0] + nv1[1]); sai = (ni[0] + ni[1]) + (ni1[0] + ni1[1]);
;         const unsigned cbo = base + (unsigned)s * 512u;
	ds_read_b128 v[148:151], v76 offset:1024
	ds_read_b128 v[152:155], v76 offset:1056
	ds_read_b128 v[156:159], v76 offset:1088
	ds_read_b128 v[160:163], v76 offset:1120
	ds_read_b128 v[164:167], v76 offset:1280
	ds_read_b128 v[168:171], v76 offset:1312
	ds_read_b128 v[172:175], v76 offset:1344
	ds_read_b128 v[176:179], v76 offset:1376
	global_load_ushort v88, v72, s[4:5] offset:0
	global_load_ushort v89, v72, s[0:1] offset:0
	global_load_ushort v90, v72, s[12:13] offset:1024
	global_load_ushort v91, v[74:75], off offset:0
	global_load_ushort v92, v[74:75], off offset:64
	global_load_ushort v93, v72, s[2:3] offset:0
	v_mfma_f32_32x32x2_f32 v[0:15], v240, v244, v[0:15]
	v_mfma_f32_32x32x2_f32 v[32:47], v240, v245, v[32:47]
	ds_read_b128 v[192:195], v76 offset:1152
	ds_read_b128 v[196:199], v76 offset:1184
	ds_read_b128 v[200:203], v76 offset:1216
	ds_read_b128 v[204:207], v76 offset:1248
	ds_read_b128 v[208:211], v76 offset:1408
	ds_read_b128 v[212:215], v76 offset:1440
	ds_read_b128 v[216:219], v76 offset:1472
	ds_read_b128 v[220:223], v76 offset:1504
	v_mfma_f32_32x32x2_f32 v[16:31], v241, v244, v[16:31]
	v_mfma_f32_32x32x2_f32 v[48:63], v241, v245, v[48:63]
	s_waitcnt vmcnt(21)
	v_lshlrev_b32_e32 v78, 16, v224
	v_mul_f32_e32 v78, 0xbfb8aa3b, v78
	v_exp_f32_e32 v78, v78
	v_lshlrev_b32_e32 v79, 16, v225
	v_lshlrev_b32_e32 v80, 16, v226
	v_mul_f32_e32 v246, v246, v78
	v_mul_f32_e32 v79, v79, v246
	v_mul_f32_e32 v80, v80, v246
	v_rcp_f32_e32 v248, v246
	s_nop 0
	ds_write2st64_b32 v77, v248, v79 offset0:0 offset1:1
	ds_write_b32 v77, v80 offset:512
	s_waitcnt lgkmcnt(10)
	v_pk_mul_f32 v[64:65], v[0:1], v[148:149]
	v_pk_mul_f32 v[68:69], v[0:1], v[164:165]
	v_pk_fma_f32 v[64:65], v[2:3], v[150:151], v[64:65]
	v_pk_fma_f32 v[68:69], v[2:3], v[166:167], v[68:69]
	v_pk_fma_f32 v[64:65], v[4:5], v[152:153], v[64:65]
	v_pk_fma_f32 v[68:69], v[4:5], v[168:169], v[68:69]
	v_pk_fma_f32 v[64:65], v[6:7], v[154:155], v[64:65]
	v_pk_fma_f32 v[68:69], v[6:7], v[170:171], v[68:69]
	v_pk_fma_f32 v[64:65], v[8:9], v[156:157], v[64:65]
	v_pk_fma_f32 v[68:69], v[8:9], v[172:173], v[68:69]
	v_pk_fma_f32 v[64:65], v[10:11], v[158:159], v[64:65]
	v_pk_fma_f32 v[68:69], v[10:11], v[174:175], v[68:69]
	v_pk_fma_f32 v[64:65], v[12:13], v[160:161], v[64:65]
	v_pk_fma_f32 v[68:69], v[12:13], v[176:177], v[68:69]
	v_pk_fma_f32 v[64:65], v[14:15], v[162:163], v[64:65]
	v_pk_fma_f32 v[68:69], v[14:15], v[178:179], v[68:69]
	v_pk_mul_f32 v[66:67], v[32:33], v[148:149]
	v_pk_mul_f32 v[70:71], v[32:33], v[164:165]
	v_pk_fma_f32 v[66:67], v[34:35], v[150:151], v[66:67]
	v_pk_fma_f32 v[70:71], v[34:35], v[166:167], v[70:71]
	v_pk_fma_f32 v[66:67], v[36:37], v[152:153], v[66:67]
	v_pk_fma_f32 v[70:71], v[36:37], v[168:169], v[70:71]
	v_pk_fma_f32 v[66:67], v[38:39], v[154:155], v[66:67]
	v_pk_fma_f32 v[70:71], v[38:39], v[170:171], v[70:71]
	v_pk_fma_f32 v[66:67], v[40:41], v[156:157], v[66:67]
	v_pk_fma_f32 v[70:71], v[40:41], v[172:173], v[70:71]
	v_pk_fma_f32 v[66:67], v[42:43], v[158:159], v[66:67]
	v_pk_fma_f32 v[70:71], v[42:43], v[174:175], v[70:71]
	v_pk_fma_f32 v[66:67], v[44:45], v[160:161], v[66:67]
	v_pk_fma_f32 v[70:71], v[44:45], v[176:177], v[70:71]
	v_pk_fma_f32 v[66:67], v[46:47], v[162:163], v[66:67]
	v_pk_fma_f32 v[70:71], v[46:47], v[178:179], v[70:71]
	s_waitcnt lgkmcnt(2)
	v_pk_fma_f32 v[64:65], v[16:17], v[192:193], v[64:65]
	v_pk_fma_f32 v[68:69], v[16:17], v[208:209], v[68:69]
	v_pk_fma_f32 v[64:65], v[18:19], v[194:195], v[64:65]
	v_pk_fma_f32 v[68:69], v[18:19], v[210:211], v[68:69]
	v_pk_fma_f32 v[64:65], v[20:21], v[196:197], v[64:65]
	v_pk_fma_f32 v[68:69], v[20:21], v[212:213], v[68:69]
	v_pk_fma_f32 v[64:65], v[22:23], v[198:199], v[64:65]
	v_pk_fma_f32 v[68:69], v[22:23], v[214:215], v[68:69]
	v_pk_fma_f32 v[64:65], v[24:25], v[200:201], v[64:65]
	v_pk_fma_f32 v[68:69], v[24:25], v[216:217], v[68:69]
	v_pk_fma_f32 v[64:65], v[26:27], v[202:203], v[64:65]
	v_pk_fma_f32 v[68:69], v[26:27], v[218:219], v[68:69]
	v_pk_fma_f32 v[64:65], v[28:29], v[204:205], v[64:65]
	v_pk_fma_f32 v[68:69], v[28:29], v[220:221], v[68:69]
	v_pk_fma_f32 v[64:65], v[30:31], v[206:207], v[64:65]
	v_pk_fma_f32 v[68:69], v[30:31], v[222:223], v[68:69]
	v_pk_fma_f32 v[66:67], v[48:49], v[192:193], v[66:67]
	v_pk_fma_f32 v[70:71], v[48:49], v[208:209], v[70:71]
	v_pk_fma_f32 v[66:67], v[50:51], v[194:195], v[66:67]
	v_pk_fma_f32 v[70:71], v[50:51], v[210:211], v[70:71]
	v_pk_fma_f32 v[66:67], v[52:53], v[196:197], v[66:67]
	v_pk_fma_f32 v[70:71], v[52:53], v[212:213], v[70:71]
	v_pk_fma_f32 v[66:67], v[54:55], v[198:199], v[66:67]
	v_pk_fma_f32 v[70:71], v[54:55], v[214:215], v[70:71]
	v_pk_fma_f32 v[66:67], v[56:57], v[200:201], v[66:67]
	v_pk_fma_f32 v[70:71], v[56:57], v[216:217], v[70:71]
	v_pk_fma_f32 v[66:67], v[58:59], v[202:203], v[66:67]
	v_pk_fma_f32 v[70:71], v[58:59], v[218:219], v[70:71]
	v_pk_fma_f32 v[66:67], v[60:61], v[204:205], v[66:67]
	v_pk_fma_f32 v[70:71], v[60:61], v[220:221], v[70:71]
	v_pk_fma_f32 v[66:67], v[62:63], v[206:207], v[66:67]
	v_pk_fma_f32 v[70:71], v[62:63], v[222:223], v[70:71]
	ds_read_b32 v249, v251 offset:0
	ds_read_b32 v250, v251 offset:128
	v_lshlrev_b32_e32 v240, 16, v227
	v_lshlrev_b32_e32 v241, 16, v228
	s_waitcnt lgkmcnt(0)
	v_mul_f32_e32 v240, v240, v249
	v_mul_f32_e32 v241, v241, v250
	v_add_f32_e32 v68, v68, v69
	v_add_f32_e32 v70, v70, v71
	v_add_f32_e32 v64, v64, v65
	v_add_f32_e32 v66, v66, v67
	v_lshlrev_b32_e32 v245, 16, v229
	v_permlane32_swap_b32_e32 v68, v70
	v_permlane32_swap_b32_e32 v64, v66
	v_add_f32_e32 v244, v68, v70
	v_add_f32_e32 v64, v64, v66
	v_bfe_u32 v66, v64, 16, 1
	v_add3_u32 v66, v64, v66, s69
	v_permlane32_swap_b32_e32 v244, v245
	global_store_short_d16_hi v72, v66, s[22:23] offset:-4096
	v_add_u32_e32 v72, 0x400, v72
	v_lshl_add_u64 v[74:75], v[74:75], 0, s[54:55]
	s_branch .Lscan_s_s3e

; __device__ void phase_rwkv_scan(const Ctx& p, int l, LAS unsigned char* lds) {
;     ...
;             rwkv_scan<false>(R, EW, K, V, A, B, (unsigned)((T_P + s * 32) * 512 + h * 64 + lane), 32, Sv, Si, YH, QH, L, lane);
;             float* op = p.out + O_RWS + so;
; #pragma unroll
;             for (int i = 0; i < 32; i += 2) *(float4*)(op + 2 * i) = make_float4(Sv[i][0], Sv[i][1], Sv[i + 1][0], Sv[i + 1][1]);
.Lscan_s_s3e:
	s_add_i32 s41, s41, 1
	s_cmpk_lg_i32 s41, 8
	s_cbranch_scc1 .Lscan_s_loop
	s_waitcnt vmcnt(0) lgkmcnt(0)
	s_mov_b64 s[14:15], s[36:37]
	v_and_b32_e32 v79, 31, v139
	v_lshrrev_b32_e32 v78, 5, v139
	v_lshlrev_b32_e32 v79, 8, v79
	v_lshl_add_u32 v79, v78, 4, v79
	v_add_u32_e32 v80, 0x2000, v79
	global_store_dwordx4 v79, v[0:3], s[14:15] offset:0
	global_store_dwordx4 v79, v[4:7], s[14:15] offset:32
	global_store_dwordx4 v79, v[8:11], s[14:15] offset:64
	global_store_dwordx4 v79, v[12:15], s[14:15] offset:96
	global_store_dwordx4 v79, v[16:19], s[14:15] offset:128
	global_store_dwordx4 v79, v[20:23], s[14:15] offset:160
	global_store_dwordx4 v79, v[24:27], s[14:15] offset:192
	global_store_dwordx4 v79, v[28:31], s[14:15] offset:224
	global_store_dwordx4 v80, v[32:35], s[14:15] offset:0
	global_store_dwordx4 v80, v[36:39], s[14:15] offset:32
	global_store_dwordx4 v80, v[40:43], s[14:15] offset:64
	global_store_dwordx4 v80, v[44:47], s[14:15] offset:96
	global_store_dwordx4 v80, v[48:51], s[14:15] offset:128
	global_store_dwordx4 v80, v[52:55], s[14:15] offset:160
	global_store_dwordx4 v80, v[56:59], s[14:15] offset:192
	global_store_dwordx4 v80, v[60:63], s[14:15] offset:224
	s_branch .LBB0_591
